# attention loop: next-tile scores stay in v[64:79] across the back edge (16 v_mov per 2 steps removed; step A staging regs and K fragments renamed to free registers)
# baseline (speedup 1.0000x reference)
.LBB0_198:
	v_or_b32_e32 v0, s61, v98
	v_readlane_b32 s68, v254, 23
	v_ashrrev_i32_e32 v1, 31, v0
	v_readlane_b32 s80, v254, 35
	v_readlane_b32 s81, v254, 36
	s_lshr_b32 s15, s54, 2
	s_and_b32 s14, s15, s14
	v_lshl_add_u64 v[0:1], v[0:1], 2, s[80:81]
	global_load_dword v2, v[0:1], off
	s_and_b32 s15, s5, 1
	s_lshl_b32 s5, s16, 12
	s_lshl_b32 s18, s54, 6
	s_add_i32 s24, s5, 0x8000
	s_lshl_b32 s5, s15, 8
	s_and_b32 s18, s18, 0xc0
	s_or_b32 s5, s5, s18
	s_lshl_b32 s17, s16, 13
	s_lshl_b32 s18, s5, 1
	s_add_u32 s18, s58, s18
	s_addc_u32 s19, s59, 0
	s_lshl_b32 s15, s15, 7
	v_readlane_b32 s26, v255, 10
	v_readlane_b32 s27, v255, 11
	s_add_u32 s54, s26, s15
	s_addc_u32 s55, s27, 0
	v_readlane_b32 s26, v255, 6
	v_readlane_b32 s27, v255, 7
	s_add_u32 s56, s26, s15
	s_addc_u32 s57, s27, 0
	s_lshl_b32 s14, s14, 8
	s_cmp_lt_i32 s16, 8
	s_cselect_b32 s16, s17, s24
	v_ashrrev_i32_e32 v0, 1, v97
	s_movk_i32 s15, 0xffe0
	v_and_or_b32 v0, v0, s15, v195
	s_cselect_b32 s15, 0x7d, 61
	s_add_i32 s14, s16, s14
	v_add_u32_e32 v0, s14, v0
	v_ashrrev_i32_e32 v1, 31, v0
	v_lshlrev_b64 v[0:1], 10, v[0:1]
	v_lshl_add_u64 v[0:1], s[18:19], 0, v[0:1]
	v_lshlrev_b32_e32 v168, 4, v193
	v_lshl_add_u64 v[0:1], v[0:1], 0, v[168:169]
	global_load_dwordx4 v[120:123], v[0:1], off
	global_load_dwordx4 v[116:119], v[0:1], off offset:32
	global_load_dwordx4 v[112:115], v[0:1], off offset:64
	global_load_dwordx4 v[124:127], v[0:1], off offset:96
	v_and_b32_e32 v3, 64, v182
	s_waitcnt vmcnt(10)
	v_xor_b32_e32 v4, 32, v182
	v_add_u32_e32 v3, 64, v3
	v_cmp_lt_i32_e32 vcc, v4, v3
	v_xor_b32_e32 v5, 16, v182
	v_xor_b32_e32 v6, 8, v182
	v_cndmask_b32_e32 v4, v182, v4, vcc
	v_cmp_lt_i32_e32 vcc, v5, v3
	v_lshlrev_b32_e32 v168, 2, v4
	v_xor_b32_e32 v7, 4, v182
	v_cndmask_b32_e32 v5, v182, v5, vcc
	v_cmp_lt_i32_e32 vcc, v6, v3
	s_waitcnt vmcnt(8)
	v_xor_b32_e32 v8, 2, v182
	v_xor_b32_e32 v9, 1, v182
	v_cndmask_b32_e32 v6, v182, v6, vcc
	v_cmp_lt_i32_e32 vcc, v7, v3
	v_ashrrev_i32_e32 v10, 3, v97
	v_and_b32_e32 v11, 7, v97
	v_cndmask_b32_e32 v7, v182, v7, vcc
	v_cmp_lt_i32_e32 vcc, v8, v3
	v_lshlrev_b32_e32 v11, 4, v11
	v_lshlrev_b32_e32 v60, 7, v195
	v_cndmask_b32_e32 v0, v182, v8, vcc
	v_cmp_lt_i32_e32 vcc, v9, v3
	s_waitcnt vmcnt(6)
	v_lshlrev_b32_e32 v12, 2, v0
	v_lshlrev_b32_e32 v3, 2, v5
	v_cndmask_b32_e32 v1, v182, v9, vcc
	v_lshlrev_b32_e32 v13, 2, v1
	v_lshlrev_b32_e32 v8, 2, v6
	v_lshlrev_b32_e32 v9, 2, v7
	v_lshlrev_b32_e32 v64, 4, v97
	v_bfe_u32 v61, v97, 1, 3
	v_and_b32_e32 v200, 0xc0, v64
	v_mov_b32_e32 v197, 0
	s_mov_b32 s17, 0
	v_readlane_b32 s69, v254, 24
	v_readlane_b32 s70, v254, 25
	v_readlane_b32 s71, v254, 26
	v_readlane_b32 s72, v254, 27
	v_readlane_b32 s73, v254, 28
	v_readlane_b32 s74, v254, 29
	v_readlane_b32 s75, v254, 30
	s_waitcnt vmcnt(4)
	v_and_b32_e32 v4, 0x7fffffff, v2
	ds_bpermute_b32 v4, v168, v4
	v_max_f32_e64 v0, |v2|, |v2|
	v_readlane_b32 s76, v254, 31
	v_readlane_b32 s77, v254, 32
	v_readlane_b32 s78, v254, 33
	s_waitcnt lgkmcnt(0)
	v_max_f32_e32 v1, v4, v4
	v_max_f32_e32 v14, v0, v1
	v_add_u32_e32 v0, s16, v10
	v_lshl_or_b32 v198, v0, 8, v11
	ds_bpermute_b32 v15, v3, v14
	global_load_dwordx4 v[0:3], v198, s[54:55]
	global_load_dwordx4 v[4:7], v198, s[56:57]
	v_add_u32_e32 v204, 0x4000, v198
	global_load_dwordx4 v[48:51], v204, s[54:55]
	s_mov_b32 s16, 0xf800000
	s_waitcnt lgkmcnt(0)
	v_max_f32_e32 v11, v15, v15
	v_max_f32_e32 v11, v14, v11
	ds_bpermute_b32 v8, v8, v11
	v_readlane_b32 s79, v254, 34
	v_readlane_b32 s82, v254, 37
	v_readlane_b32 s83, v254, 38
	s_waitcnt lgkmcnt(0)
	v_max_f32_e32 v8, v8, v8
	v_max_f32_e32 v8, v11, v8
	ds_bpermute_b32 v9, v9, v8
	s_waitcnt lgkmcnt(0)
	v_max_f32_e32 v9, v9, v9
	v_max_f32_e32 v8, v8, v9
	ds_bpermute_b32 v9, v12, v8
	s_waitcnt vmcnt(6)
	v_and_b32_e32 v15, 0xffff0000, v120
	v_lshlrev_b32_e32 v14, 16, v120
	v_mul_f32_e32 v15, v15, v15
	v_lshlrev_b32_e32 v16, 16, v121
	v_fmac_f32_e32 v15, v14, v14
	v_and_b32_e32 v17, 0xffff0000, v121
	v_fmac_f32_e32 v15, v16, v16
	v_lshlrev_b32_e32 v18, 16, v122
	v_fmac_f32_e32 v15, v17, v17
	v_and_b32_e32 v19, 0xffff0000, v122
	v_fmac_f32_e32 v15, v18, v18
	v_lshlrev_b32_e32 v20, 16, v123
	v_fmac_f32_e32 v15, v19, v19
	v_and_b32_e32 v21, 0xffff0000, v123
	v_fmac_f32_e32 v15, v20, v20
	s_waitcnt vmcnt(5)
	v_lshlrev_b32_e32 v22, 16, v116
	v_fmac_f32_e32 v15, v21, v21
	v_and_b32_e32 v23, 0xffff0000, v116
	v_fmac_f32_e32 v15, v22, v22
	v_lshlrev_b32_e32 v24, 16, v117
	v_fmac_f32_e32 v15, v23, v23
	v_and_b32_e32 v25, 0xffff0000, v117
	v_fmac_f32_e32 v15, v24, v24
	v_lshlrev_b32_e32 v26, 16, v118
	v_fmac_f32_e32 v15, v25, v25
	v_and_b32_e32 v27, 0xffff0000, v118
	v_fmac_f32_e32 v15, v26, v26
	v_lshlrev_b32_e32 v28, 16, v119
	v_fmac_f32_e32 v15, v27, v27
	s_waitcnt lgkmcnt(0)
	v_max_f32_e32 v9, v9, v9
	v_fmac_f32_e32 v15, v28, v28
	v_max_f32_e32 v11, v8, v9
	v_and_b32_e32 v8, 0xffff0000, v119
	v_fmac_f32_e32 v15, v8, v8
	s_waitcnt vmcnt(4)
	v_lshlrev_b32_e32 v8, 16, v112
	v_fmac_f32_e32 v15, v8, v8
	v_and_b32_e32 v8, 0xffff0000, v112
	v_fmac_f32_e32 v15, v8, v8
	v_lshlrev_b32_e32 v8, 16, v113
	v_fmac_f32_e32 v15, v8, v8
	v_and_b32_e32 v8, 0xffff0000, v113
	v_fmac_f32_e32 v15, v8, v8
	v_lshlrev_b32_e32 v8, 16, v114
	v_fmac_f32_e32 v15, v8, v8
	v_and_b32_e32 v8, 0xffff0000, v114
	v_fmac_f32_e32 v15, v8, v8
	v_lshlrev_b32_e32 v8, 16, v115
	v_fmac_f32_e32 v15, v8, v8
	v_and_b32_e32 v8, 0xffff0000, v115
	v_fmac_f32_e32 v15, v8, v8
	s_waitcnt vmcnt(3)
	v_and_b32_e32 v9, 0xffff0000, v124
	v_lshlrev_b32_e32 v8, 16, v124
	v_pk_mul_f32 v[8:9], v[8:9], v[8:9]
	ds_bpermute_b32 v12, v13, v11
	v_add_f32_e32 v8, v8, v15
	v_add_f32_e32 v13, v9, v8
	v_and_b32_e32 v9, 0xffff0000, v125
	v_lshlrev_b32_e32 v8, 16, v125
	v_pk_mul_f32 v[8:9], v[8:9], v[8:9]
	v_lshrrev_b32_e32 v15, 1, v97
	v_add_f32_e32 v8, v8, v13
	v_add_f32_e32 v13, v9, v8
	v_and_b32_e32 v9, 0xffff0000, v126
	v_lshlrev_b32_e32 v8, 16, v126
	v_pk_mul_f32 v[8:9], v[8:9], v[8:9]
	v_bitop3_b32 v15, v193, v15, 7 bitop3:0x78
	v_add_f32_e32 v8, v8, v13
	v_add_f32_e32 v13, v9, v8
	v_and_b32_e32 v9, 0xffff0000, v127
	v_lshlrev_b32_e32 v8, 16, v127
	v_pk_mul_f32 v[8:9], v[8:9], v[8:9]
	v_lshl_or_b32 v201, v15, 4, v60
	v_add_f32_e32 v8, v8, v13
	v_add_f32_e32 v8, v9, v8
	ds_bpermute_b32 v9, v168, v8
	s_waitcnt lgkmcnt(1)
	v_max_f32_e32 v12, v12, v12
	v_max_f32_e32 v11, v11, v12
	v_lshlrev_b32_e32 v12, 10, v97
	v_and_b32_e32 v13, 48, v64
	s_waitcnt lgkmcnt(0)
	v_add_f32_e32 v8, v8, v9
	v_mul_f32_e32 v14, 0x4f800000, v8
	v_cmp_gt_f32_e32 vcc, s16, v8
	v_lshrrev_b32_e32 v9, 1, v10
	v_xor_b32_e32 v9, v9, v97
	v_cndmask_b32_e32 v8, v8, v14, vcc
	v_sqrt_f32_e32 v14, v8
	v_lshlrev_b32_e32 v9, 4, v9
	s_movk_i32 s16, 0x70
	v_and_b32_e32 v12, 0x1000, v12
	v_add_u32_e32 v15, -1, v14
	v_fma_f32 v16, -v15, v14, v8
	v_cmp_ge_f32_e64 s[42:43], 0, v16
	v_add_u32_e32 v16, 1, v14
	v_mul_f32_e32 v11, 0x41000000, v11
	v_cndmask_b32_e64 v15, v14, v15, s[42:43]
	v_fma_f32 v14, -v16, v14, v8
	v_cmp_lt_f32_e64 s[42:43], 0, v14
	v_mul_f32_e32 v11, 0xbf8147ae, v11
	s_nop 0
	v_cndmask_b32_e64 v14, v15, v16, s[42:43]
	v_mul_f32_e32 v15, 0x37800000, v14
	v_cndmask_b32_e32 v14, v14, v15, vcc
	v_cmp_class_f32_e32 vcc, v8, v173
	s_nop 1
	v_cndmask_b32_e32 v8, v14, v8, vcc
	v_lshlrev_b32_e32 v14, 7, v10
	v_and_or_b32 v202, v9, s16, v14
	s_waitcnt vmcnt(2)
	ds_write_b128 v202, v[0:3]
	v_lshl_or_b32 v0, v10, 6, v13
	v_add_u32_e32 v196, v0, v12
	s_waitcnt vmcnt(1)
	ds_write_b128 v196, v[4:7] offset:16384
	s_waitcnt lgkmcnt(0)
	s_barrier
	ds_read_b128 v[0:3], v201
	ds_read_b128 v[52:55], v201 offset:4096
	v_mul_f32_e32 v32, v11, v8
	v_mov_b32_e32 v33, v32
	v_mov_b32_e32 v34, v32
	v_mov_b32_e32 v35, v32
	v_mov_b32_e32 v36, v32
	v_mov_b32_e32 v37, v32
	v_mov_b32_e32 v38, v32
	v_mov_b32_e32 v39, v32
	v_mov_b32_e32 v40, v32
	v_mov_b32_e32 v41, v32
	v_mov_b32_e32 v42, v32
	v_mov_b32_e32 v43, v32
	v_mov_b32_e32 v44, v32
	v_mov_b32_e32 v45, v32
	v_mov_b32_e32 v46, v32
	v_mov_b32_e32 v47, v32
	s_mov_b32 s16, 0
	s_waitcnt lgkmcnt(1)
	v_mfma_f32_32x32x16_bf16 v[16:31], v[0:3], v[120:123], v[32:47]
	v_bitop3_b32 v0, v193, v61, 2 bitop3:0x36
	v_lshl_or_b32 v206, v0, 4, v60
	s_waitcnt lgkmcnt(0)
	v_mfma_f32_32x32x16_bf16 v[0:15], v[52:55], v[120:123], v[32:47]
	ds_read_b128 v[52:55], v206
	ds_read_b128 v[56:59], v206 offset:4096
	s_waitcnt lgkmcnt(1)
	v_mfma_f32_32x32x16_bf16 v[16:31], v[52:55], v[116:119], v[16:31]
	v_bitop3_b32 v52, v193, v61, 4 bitop3:0x36
	v_lshl_or_b32 v203, v52, 4, v60
	s_waitcnt lgkmcnt(0)
	v_mfma_f32_32x32x16_bf16 v[0:15], v[56:59], v[116:119], v[0:15]
	ds_read_b128 v[52:55], v203
	ds_read_b128 v[56:59], v203 offset:4096
	s_waitcnt lgkmcnt(1)
	v_mfma_f32_32x32x16_bf16 v[16:31], v[52:55], v[112:115], v[16:31]
	v_bitop3_b32 v52, v193, v61, 6 bitop3:0x36
	v_lshl_or_b32 v205, v52, 4, v60
	s_waitcnt lgkmcnt(0)
	v_mfma_f32_32x32x16_bf16 v[0:15], v[56:59], v[112:115], v[0:15]
	ds_read_b128 v[52:55], v205
	ds_read_b128 v[56:59], v205 offset:4096
	s_waitcnt vmcnt(0)
	ds_write_b128 v202, v[48:51] offset:8192
	s_waitcnt lgkmcnt(0)
	s_barrier
	v_mfma_f32_32x32x16_bf16 v[16:31], v[52:55], v[124:127], v[16:31]
	v_mfma_f32_32x32x16_bf16 v[0:15], v[56:59], v[124:127], v[0:15]
	s_nop 10
	v_exp_f32_e32 v48, v16
	v_exp_f32_e32 v49, v17
	v_exp_f32_e32 v50, v18
	v_exp_f32_e32 v51, v19
	v_exp_f32_e32 v52, v20
	v_exp_f32_e32 v53, v21
	v_exp_f32_e32 v54, v22
	v_exp_f32_e32 v55, v23
	v_exp_f32_e32 v56, v24
	v_exp_f32_e32 v57, v25
	v_exp_f32_e32 v58, v26
	v_exp_f32_e32 v59, v27
	v_exp_f32_e32 v60, v28
	v_exp_f32_e32 v61, v29
	v_exp_f32_e32 v62, v30
	v_exp_f32_e32 v63, v31
	v_exp_f32_e32 v162, v0
	v_exp_f32_e32 v164, v1
	v_exp_f32_e32 v165, v2
	v_exp_f32_e32 v163, v3
	v_exp_f32_e32 v156, v4
	v_exp_f32_e32 v160, v5
	v_exp_f32_e32 v161, v6
	v_exp_f32_e32 v157, v7
	v_exp_f32_e32 v136, v8
	v_exp_f32_e32 v140, v9
	v_exp_f32_e32 v141, v10
	v_exp_f32_e32 v137, v11
	v_exp_f32_e32 v128, v12
	v_exp_f32_e32 v132, v13
	v_exp_f32_e32 v133, v14
	v_exp_f32_e32 v129, v15
	v_and_b32_e32 v0, 16, v97
	v_lshlrev_b32_e32 v1, 2, v98
	v_and_or_b32 v0, v1, 12, v0
	v_lshlrev_b32_e32 v199, 1, v0
	v_lshl_or_b32 v0, v193, 8, v200
	v_add_u32_e32 v207, v199, v0
	v_mov_b32_e32 v16, 0
	v_mov_b32_e32 v17, v197
	v_mov_b32_e32 v18, v197
	v_mov_b32_e32 v19, v197
	v_mov_b32_e32 v20, v197
	v_mov_b32_e32 v21, v197
	v_mov_b32_e32 v22, v197
	v_mov_b32_e32 v23, v197
	v_mov_b32_e32 v24, v197
	v_mov_b32_e32 v25, v197
	v_mov_b32_e32 v26, v197
	v_mov_b32_e32 v27, v197
	v_mov_b32_e32 v28, v197
	v_mov_b32_e32 v29, v197
	v_mov_b32_e32 v30, v197
	v_mov_b32_e32 v31, v197
	v_mov_b32_e32 v0, 0
	v_mov_b32_e32 v1, v197
	v_mov_b32_e32 v2, v197
	v_mov_b32_e32 v3, v197
	v_mov_b32_e32 v4, v197
	v_mov_b32_e32 v5, v197
	v_mov_b32_e32 v6, v197
	v_mov_b32_e32 v7, v197
	v_mov_b32_e32 v8, v197
	v_mov_b32_e32 v9, v197
	v_mov_b32_e32 v10, v197
	v_mov_b32_e32 v11, v197
	v_mov_b32_e32 v12, v197
	v_mov_b32_e32 v13, v197
	v_mov_b32_e32 v14, v197
	v_mov_b32_e32 v15, v197
	v_mov_b32_e32 v64, v162
	v_mov_b32_e32 v65, v164
	v_mov_b32_e32 v66, v165
	v_mov_b32_e32 v67, v163
	v_mov_b32_e32 v68, v156
	v_mov_b32_e32 v69, v160
	v_mov_b32_e32 v70, v161
	v_mov_b32_e32 v71, v157
	v_mov_b32_e32 v72, v136
	v_mov_b32_e32 v73, v140
	v_mov_b32_e32 v74, v141
	v_mov_b32_e32 v75, v137
	v_mov_b32_e32 v76, v128
	v_mov_b32_e32 v77, v132
	v_mov_b32_e32 v78, v133
	v_mov_b32_e32 v79, v129
.LBB0_199:
	v_add_u32_e32 v166, s16, v198
	v_add_u32_e32 v167, 0x8000, v166
	v_add_u32_e32 v240, 0x4000, v166
	global_load_dwordx4 v[224:227], v167, s[54:55]
	s_add_i32 s17, s17, 2
	global_load_dwordx4 v[228:231], v240, s[56:57]
	ds_read_b128 v[232:235], v201 offset:8192
	ds_read_b128 v[236:239], v201 offset:12288
	ds_read_b128 v[208:211], v206 offset:8192
	ds_read_b128 v[212:215], v206 offset:12288
	s_setprio 1
	s_waitcnt lgkmcnt(3)
	v_mfma_f32_32x32x16_bf16 v[96:111], v[232:235], v[120:123], v[32:47]
	s_setprio 0
	v_cvt_pk_bf16_f32 v144, v48, v49
	v_add_f32_e32 v48, v48, v49
	v_add_f32_e32 v49, v50, v51
	v_add_f32_e32 v48, v48, v49
	v_cvt_pk_bf16_f32 v145, v50, v51
	v_add_f32_e32 v48, 0, v48
	s_setprio 1
	s_waitcnt lgkmcnt(2)
	v_mfma_f32_32x32x16_bf16 v[80:95], v[236:239], v[120:123], v[32:47]
	s_setprio 0
	v_add_f32_e32 v49, v52, v53
	v_add_f32_e32 v50, v54, v55
	v_add_f32_e32 v49, v49, v50
	v_cvt_pk_bf16_f32 v146, v52, v53
	v_cvt_pk_bf16_f32 v147, v54, v55
	v_add_f32_e32 v152, v49, v48
	ds_read_b128 v[48:51], v203 offset:8192
	ds_read_b128 v[52:55], v203 offset:12288
	ds_read_b128 v[232:235], v205 offset:8192
	ds_read_b128 v[236:239], v205 offset:12288
	s_setprio 1
	s_waitcnt lgkmcnt(5)
	v_mfma_f32_32x32x16_bf16 v[96:111], v[208:211], v[116:119], v[96:111]
	s_setprio 0
	v_cvt_pk_bf16_f32 v148, v56, v57
	v_add_f32_e32 v56, v56, v57
	v_add_f32_e32 v57, v58, v59
	v_add_f32_e32 v56, v56, v57
	v_cvt_pk_bf16_f32 v149, v58, v59
	v_add_f32_e32 v56, v56, v152
	s_setprio 1
	s_waitcnt lgkmcnt(4)
	v_mfma_f32_32x32x16_bf16 v[80:95], v[212:215], v[116:119], v[80:95]
	s_setprio 0
	v_add_f32_e32 v57, v60, v61
	v_add_f32_e32 v58, v62, v63
	v_add_f32_e32 v57, v57, v58
	v_cvt_pk_bf16_f32 v150, v60, v61
	v_cvt_pk_bf16_f32 v151, v62, v63
	v_add_f32_e32 v56, v57, v56
	s_setprio 1
	s_waitcnt lgkmcnt(3)
	v_mfma_f32_32x32x16_bf16 v[96:111], v[48:51], v[112:115], v[96:111]
	s_setprio 0
	v_add_f32_e64 v48, v65, v64
	v_add_f32_e64 v49, v66, v67
	v_cvt_pk_bf16_f32 v152, v64, v65
	v_add_f32_e32 v48, v48, v49
	v_cvt_pk_bf16_f32 v153, v66, v67
	v_add_f32_e32 v50, v48, v56
	s_setprio 1
	s_waitcnt lgkmcnt(2)
	v_mfma_f32_32x32x16_bf16 v[80:95], v[52:55], v[112:115], v[80:95]
	s_setprio 0
	v_add_f32_e64 v48, v69, v68
	v_add_f32_e64 v49, v70, v71
	v_cvt_pk_bf16_f32 v154, v68, v69
	v_add_f32_e32 v48, v48, v49
	v_cvt_pk_bf16_f32 v155, v70, v71
	v_add_f32_e32 v50, v48, v50
	s_setprio 1
	s_waitcnt lgkmcnt(1)
	v_mfma_f32_32x32x16_bf16 v[96:111], v[232:235], v[124:127], v[96:111]
	s_setprio 0
	v_add_f32_e64 v48, v73, v72
	v_add_f32_e64 v49, v74, v75
	v_cvt_pk_bf16_f32 v156, v72, v73
	v_add_f32_e32 v48, v48, v49
	v_cvt_pk_bf16_f32 v157, v74, v75
	v_add_f32_e32 v50, v48, v50
	s_setprio 1
	s_waitcnt lgkmcnt(0)
	v_mfma_f32_32x32x16_bf16 v[80:95], v[236:239], v[124:127], v[80:95]
	s_setprio 0
	v_add_f32_e64 v48, v77, v76
	v_add_f32_e64 v49, v78, v79
	v_cvt_pk_bf16_f32 v158, v76, v77
	v_add_f32_e32 v48, v48, v49
	v_cvt_pk_bf16_f32 v159, v78, v79
	v_add_f32_e32 v180, v48, v50
	ds_read_b64_tr_b16 v[48:49], v207 offset:16384
	ds_read_b64_tr_b16 v[50:51], v207 offset:16896
	ds_read_b64_tr_b16 v[52:53], v207 offset:17408
	ds_read_b64_tr_b16 v[54:55], v207 offset:17920
	ds_read_b64_tr_b16 v[56:57], v207 offset:20480
	ds_read_b64_tr_b16 v[58:59], v207 offset:20992
	ds_read_b64_tr_b16 v[60:61], v207 offset:21504
	ds_read_b64_tr_b16 v[62:63], v207 offset:22016
	s_setprio 1
	s_waitcnt lgkmcnt(6)
	v_mfma_f32_32x32x16_bf16 v[16:31], v[48:51], v[144:147], v[16:31]
	s_setprio 0
	v_exp_f32_e32 v96, v96
	v_exp_f32_e32 v97, v97
	v_exp_f32_e32 v98, v98
	v_exp_f32_e32 v99, v99
	s_setprio 1
	s_waitcnt lgkmcnt(2)
	v_mfma_f32_32x32x16_bf16 v[0:15], v[56:59], v[144:147], v[0:15]
	s_setprio 0
	v_exp_f32_e32 v100, v100
	v_exp_f32_e32 v101, v101
	v_exp_f32_e32 v102, v102
	v_exp_f32_e32 v103, v103
	ds_read_b64_tr_b16 v[48:49], v207 offset:18432
	ds_read_b64_tr_b16 v[50:51], v207 offset:18944
	ds_read_b64_tr_b16 v[56:57], v207 offset:19456
	ds_read_b64_tr_b16 v[58:59], v207 offset:19968
	ds_read_b64_tr_b16 v[72:73], v207 offset:22528
	ds_read_b64_tr_b16 v[74:75], v207 offset:23040
	ds_read_b64_tr_b16 v[76:77], v207 offset:23552
	ds_read_b64_tr_b16 v[78:79], v207 offset:24064
	s_setprio 1
	v_mfma_f32_32x32x16_bf16 v[16:31], v[52:55], v[148:151], v[16:31]
	s_setprio 0
	v_exp_f32_e32 v104, v104
	v_exp_f32_e32 v105, v105
	v_exp_f32_e32 v106, v106
	v_exp_f32_e32 v107, v107
	s_setprio 1
	s_waitcnt lgkmcnt(8)
	v_mfma_f32_32x32x16_bf16 v[0:15], v[60:63], v[148:151], v[0:15]
	s_setprio 0
	v_exp_f32_e32 v108, v108
	v_exp_f32_e32 v109, v109
	v_exp_f32_e32 v110, v110
	v_exp_f32_e32 v111, v111
	s_setprio 1
	s_waitcnt lgkmcnt(6)
	v_mfma_f32_32x32x16_bf16 v[16:31], v[48:51], v[152:155], v[16:31]
	s_setprio 0
	v_exp_f32_e32 v80, v80
	v_exp_f32_e32 v81, v81
	v_exp_f32_e32 v82, v82
	v_exp_f32_e32 v83, v83
	s_setprio 1
	s_waitcnt lgkmcnt(2)
	v_mfma_f32_32x32x16_bf16 v[0:15], v[72:75], v[152:155], v[0:15]
	s_setprio 0
	v_exp_f32_e32 v84, v84
	v_exp_f32_e32 v85, v85
	v_exp_f32_e32 v86, v86
	v_exp_f32_e32 v87, v87
	s_setprio 1
	v_mfma_f32_32x32x16_bf16 v[16:31], v[56:59], v[156:159], v[16:31]
	s_setprio 0
	v_exp_f32_e32 v88, v88
	v_exp_f32_e32 v89, v89
	v_exp_f32_e32 v90, v90
	v_exp_f32_e32 v91, v91
	s_setprio 1
	s_waitcnt lgkmcnt(0)
	v_mfma_f32_32x32x16_bf16 v[0:15], v[76:79], v[156:159], v[0:15]
	s_setprio 0
	v_exp_f32_e32 v92, v92
	v_exp_f32_e32 v93, v93
	v_exp_f32_e32 v94, v94
	v_exp_f32_e32 v95, v95
	v_add_u32_e32 v48, 0xc000, v166
	s_waitcnt vmcnt(1)
	ds_write_b128 v202, v[224:227]
	s_waitcnt vmcnt(0)
	ds_write_b128 v196, v[228:231] offset:24576
	s_waitcnt lgkmcnt(0)
	s_barrier
	global_load_dwordx4 v[160:163], v48, s[54:55]
	s_nop 0
	global_load_dwordx4 v[164:167], v167, s[56:57]
	ds_read_b128 v[64:67], v201
	ds_read_b128 v[208:211], v201 offset:4096
	ds_read_b128 v[212:215], v206
	ds_read_b128 v[216:219], v206 offset:4096
	s_setprio 1
	s_waitcnt lgkmcnt(3)
	v_mfma_f32_32x32x16_bf16 v[48:63], v[64:67], v[120:123], v[32:47]
	s_setprio 0
	v_add_f32_e32 v64, v96, v97
	v_add_f32_e32 v65, v98, v99
	v_add_f32_e32 v64, v64, v65
	v_cvt_pk_bf16_f32 v140, v96, v97
	v_cvt_pk_bf16_f32 v141, v98, v99
	v_add_f32_e32 v96, 0, v64
	s_setprio 1
	s_waitcnt lgkmcnt(2)
	v_mfma_f32_32x32x16_bf16 v[64:79], v[208:211], v[120:123], v[32:47]
	s_setprio 0
	v_add_f32_e32 v97, v100, v101
	v_add_f32_e32 v98, v102, v103
	v_add_f32_e32 v97, v97, v98
	v_cvt_pk_bf16_f32 v142, v100, v101
	v_cvt_pk_bf16_f32 v143, v102, v103
	v_add_f32_e32 v128, v97, v96
	ds_read_b128 v[96:99], v203
	ds_read_b128 v[100:103], v203 offset:4096
	ds_read_b128 v[208:211], v205
	ds_read_b128 v[220:223], v205 offset:4096
	s_setprio 1
	s_waitcnt lgkmcnt(5)
	v_mfma_f32_32x32x16_bf16 v[48:63], v[212:215], v[116:119], v[48:63]
	s_setprio 0
	v_cvt_pk_bf16_f32 v136, v104, v105
	v_add_f32_e32 v104, v104, v105
	v_add_f32_e32 v105, v106, v107
	v_add_f32_e32 v104, v104, v105
	v_cvt_pk_bf16_f32 v137, v106, v107
	v_add_f32_e32 v104, v104, v128
	s_setprio 1
	s_waitcnt lgkmcnt(4)
	v_mfma_f32_32x32x16_bf16 v[64:79], v[216:219], v[116:119], v[64:79]
	s_setprio 0
	v_add_f32_e32 v105, v108, v109
	v_add_f32_e32 v106, v110, v111
	v_add_f32_e32 v105, v105, v106
	v_cvt_pk_bf16_f32 v138, v108, v109
	v_cvt_pk_bf16_f32 v139, v110, v111
	v_add_f32_e32 v104, v105, v104
	s_setprio 1
	s_waitcnt lgkmcnt(3)
	v_mfma_f32_32x32x16_bf16 v[48:63], v[96:99], v[112:115], v[48:63]
	s_setprio 0
	v_cvt_pk_bf16_f32 v132, v80, v81
	v_mov_b32_e32 v96, v81
	v_mov_b32_e32 v97, v82
	v_mov_b32_e32 v81, v83
	v_pk_add_f32 v[80:81], v[96:97], v[80:81]
	v_cvt_pk_bf16_f32 v133, v82, v83
	v_add_f32_e32 v80, v80, v81
	v_add_f32_e32 v82, v80, v104
	s_setprio 1
	s_waitcnt lgkmcnt(2)
	v_mfma_f32_32x32x16_bf16 v[64:79], v[100:103], v[112:115], v[64:79]
	s_setprio 0
	v_cvt_pk_bf16_f32 v134, v84, v85
	v_mov_b32_e32 v80, v85
	v_mov_b32_e32 v81, v86
	v_mov_b32_e32 v85, v87
	v_pk_add_f32 v[80:81], v[80:81], v[84:85]
	v_cvt_pk_bf16_f32 v135, v86, v87
	v_add_f32_e32 v80, v80, v81
	v_add_f32_e32 v82, v80, v82
	s_setprio 1
	s_waitcnt lgkmcnt(1)
	v_mfma_f32_32x32x16_bf16 v[48:63], v[208:211], v[124:127], v[48:63]
	s_setprio 0
	v_cvt_pk_bf16_f32 v128, v88, v89
	v_mov_b32_e32 v80, v89
	v_mov_b32_e32 v81, v90
	v_mov_b32_e32 v89, v91
	v_pk_add_f32 v[80:81], v[80:81], v[88:89]
	v_cvt_pk_bf16_f32 v129, v90, v91
	v_add_f32_e32 v80, v80, v81
	v_add_f32_e32 v82, v80, v82
	s_setprio 1
	s_waitcnt lgkmcnt(0)
	v_mfma_f32_32x32x16_bf16 v[64:79], v[220:223], v[124:127], v[64:79]
	s_setprio 0
	v_cvt_pk_bf16_f32 v130, v92, v93
	v_mov_b32_e32 v80, v93
	v_mov_b32_e32 v81, v94
	v_mov_b32_e32 v93, v95
	v_pk_add_f32 v[80:81], v[80:81], v[92:93]
	v_cvt_pk_bf16_f32 v131, v94, v95
	v_add_f32_e32 v80, v80, v81
	v_add_f32_e32 v104, v80, v82
	ds_read_b64_tr_b16 v[80:81], v207 offset:24576
	ds_read_b64_tr_b16 v[82:83], v207 offset:25088
	ds_read_b64_tr_b16 v[84:85], v207 offset:28672
	ds_read_b64_tr_b16 v[86:87], v207 offset:29184
	ds_read_b64_tr_b16 v[88:89], v207 offset:25600
	ds_read_b64_tr_b16 v[90:91], v207 offset:26112
	ds_read_b64_tr_b16 v[92:93], v207 offset:29696
	ds_read_b64_tr_b16 v[94:95], v207 offset:30208
	v_add_f32_e32 v105, v197, v180
	s_setprio 1
	s_waitcnt lgkmcnt(6)
	v_mfma_f32_32x32x16_bf16 v[16:31], v[80:83], v[140:143], v[16:31]
	s_setprio 0
	v_exp_f32_e32 v48, v48
	v_exp_f32_e32 v49, v49
	v_exp_f32_e32 v50, v50
	v_exp_f32_e32 v51, v51
	s_setprio 1
	s_waitcnt lgkmcnt(4)
	v_mfma_f32_32x32x16_bf16 v[0:15], v[84:87], v[140:143], v[0:15]
	s_setprio 0
	v_exp_f32_e32 v52, v52
	v_exp_f32_e32 v53, v53
	v_exp_f32_e32 v54, v54
	v_exp_f32_e32 v55, v55
	ds_read_b64_tr_b16 v[80:81], v207 offset:26624
	ds_read_b64_tr_b16 v[82:83], v207 offset:27136
	ds_read_b64_tr_b16 v[84:85], v207 offset:27648
	ds_read_b64_tr_b16 v[86:87], v207 offset:28160
	ds_read_b64_tr_b16 v[96:97], v207 offset:30720
	ds_read_b64_tr_b16 v[98:99], v207 offset:31232
	ds_read_b64_tr_b16 v[100:101], v207 offset:31744
	ds_read_b64_tr_b16 v[102:103], v207 offset:32256
	s_setprio 1
	s_waitcnt lgkmcnt(10)
	v_mfma_f32_32x32x16_bf16 v[16:31], v[88:91], v[136:139], v[16:31]
	s_setprio 0
	v_exp_f32_e32 v56, v56
	v_exp_f32_e32 v57, v57
	v_exp_f32_e32 v58, v58
	v_exp_f32_e32 v59, v59
	s_setprio 1
	s_waitcnt lgkmcnt(8)
	v_mfma_f32_32x32x16_bf16 v[0:15], v[92:95], v[136:139], v[0:15]
	s_setprio 0
	v_exp_f32_e32 v60, v60
	v_exp_f32_e32 v61, v61
	v_exp_f32_e32 v62, v62
	v_exp_f32_e32 v63, v63
	s_setprio 1
	s_waitcnt lgkmcnt(6)
	v_mfma_f32_32x32x16_bf16 v[16:31], v[80:83], v[132:135], v[16:31]
	s_setprio 0
	v_exp_f32_e32 v64, v64
	v_exp_f32_e32 v65, v65
	v_exp_f32_e32 v66, v66
	v_exp_f32_e32 v67, v67
	s_setprio 1
	s_waitcnt lgkmcnt(2)
	v_mfma_f32_32x32x16_bf16 v[0:15], v[96:99], v[132:135], v[0:15]
	s_setprio 0
	v_exp_f32_e32 v68, v68
	v_exp_f32_e32 v69, v69
	v_exp_f32_e32 v70, v70
	v_exp_f32_e32 v71, v71
	s_setprio 1
	v_mfma_f32_32x32x16_bf16 v[16:31], v[84:87], v[128:131], v[16:31]
	s_setprio 0
	v_exp_f32_e32 v72, v72
	v_exp_f32_e32 v73, v73
	v_exp_f32_e32 v74, v74
	v_exp_f32_e32 v75, v75
	s_setprio 1
	s_waitcnt lgkmcnt(0)
	v_mfma_f32_32x32x16_bf16 v[0:15], v[100:103], v[128:131], v[0:15]
	s_setprio 0
	v_exp_f32_e32 v76, v76
	v_exp_f32_e32 v77, v77
	v_exp_f32_e32 v78, v78
	v_exp_f32_e32 v79, v79
	s_add_i32 s16, s16, 0x8000
	v_add_f32_e32 v197, v105, v104
	s_waitcnt vmcnt(1)
	ds_write_b128 v202, v[160:163] offset:8192
	s_waitcnt vmcnt(0)
	ds_write_b128 v196, v[164:167] offset:16384
	s_cmp_lt_u32 s17, s15
	s_waitcnt lgkmcnt(0)
	s_barrier
	s_cbranch_scc1 .LBB0_199
	v_mov_b32_e32 v162, v64
	v_mov_b32_e32 v164, v65
	v_mov_b32_e32 v165, v66
	v_mov_b32_e32 v163, v67
	v_mov_b32_e32 v156, v68
	v_mov_b32_e32 v160, v69
	v_mov_b32_e32 v161, v70
	v_mov_b32_e32 v157, v71
	v_mov_b32_e32 v136, v72
	v_mov_b32_e32 v140, v73
	v_mov_b32_e32 v141, v74
	v_mov_b32_e32 v137, v75
	v_mov_b32_e32 v128, v76
	v_mov_b32_e32 v132, v77
	v_mov_b32_e32 v133, v78
	v_mov_b32_e32 v129, v79
	v_add_u32_e32 v80, s16, v204
	global_load_dwordx4 v[96:99], v80, s[56:57]
	ds_read_b128 v[100:103], v201 offset:8192
	ds_read_b128 v[104:107], v201 offset:12288
	ds_read_b128 v[108:111], v206 offset:8192
	ds_read_b128 v[128:131], v206 offset:12288
	s_setprio 1
	s_waitcnt lgkmcnt(3)
	v_mfma_f32_32x32x16_bf16 v[80:95], v[100:103], v[120:123], v[32:47]
	s_setprio 0
	v_cvt_pk_bf16_f32 v100, v48, v49
	v_add_f32_e32 v48, v48, v49
	v_add_f32_e32 v49, v50, v51
	v_add_f32_e32 v48, v48, v49
	v_cvt_pk_bf16_f32 v101, v50, v51
	v_add_f32_e32 v48, 0, v48
	s_setprio 1
	s_waitcnt lgkmcnt(2)
	v_mfma_f32_32x32x16_bf16 v[32:47], v[104:107], v[120:123], v[32:47]
	s_setprio 0
	v_add_f32_e32 v49, v52, v53
	v_add_f32_e32 v50, v54, v55
	v_add_f32_e32 v49, v49, v50
	v_cvt_pk_bf16_f32 v102, v52, v53
	v_cvt_pk_bf16_f32 v103, v54, v55
	v_add_f32_e32 v132, v49, v48
	ds_read_b128 v[48:51], v203 offset:8192
	ds_read_b128 v[52:55], v203 offset:12288
	ds_read_b128 v[104:107], v205 offset:8192
	ds_read_b128 v[120:123], v205 offset:12288
	s_setprio 1
	s_waitcnt lgkmcnt(5)
	v_mfma_f32_32x32x16_bf16 v[80:95], v[108:111], v[116:119], v[80:95]
	s_setprio 0
	v_cvt_pk_bf16_f32 v108, v56, v57
	v_add_f32_e32 v56, v56, v57
	v_add_f32_e32 v57, v58, v59
	v_add_f32_e32 v56, v56, v57
	v_cvt_pk_bf16_f32 v109, v58, v59
	v_add_f32_e32 v56, v56, v132
	s_setprio 1
	s_waitcnt lgkmcnt(4)
	v_mfma_f32_32x32x16_bf16 v[32:47], v[128:131], v[116:119], v[32:47]
	s_setprio 0
	v_add_f32_e32 v57, v60, v61
	v_add_f32_e32 v58, v62, v63
	v_add_f32_e32 v57, v57, v58
	v_cvt_pk_bf16_f32 v110, v60, v61
	v_cvt_pk_bf16_f32 v111, v62, v63
	v_add_f32_e32 v56, v57, v56
	s_setprio 1
	s_waitcnt lgkmcnt(3)
	v_mfma_f32_32x32x16_bf16 v[80:95], v[48:51], v[112:115], v[80:95]
	s_setprio 0
	v_add_f32_e32 v50, v64, v65
	v_add_f32_e32 v51, v66, v67
	v_add_f32_e32 v50, v50, v51
	v_cvt_pk_bf16_f32 v48, v64, v65
	v_cvt_pk_bf16_f32 v49, v66, v67
	v_add_f32_e32 v56, v50, v56
	s_setprio 1
	s_waitcnt lgkmcnt(2)
	v_mfma_f32_32x32x16_bf16 v[32:47], v[52:55], v[112:115], v[32:47]
	s_setprio 0
	v_add_f32_e32 v52, v68, v69
	v_add_f32_e32 v53, v70, v71
	v_add_f32_e32 v52, v52, v53
	v_cvt_pk_bf16_f32 v50, v68, v69
	v_cvt_pk_bf16_f32 v51, v70, v71
	v_add_f32_e32 v56, v52, v56
	s_setprio 1
	s_waitcnt lgkmcnt(1)
	v_mfma_f32_32x32x16_bf16 v[80:95], v[104:107], v[124:127], v[80:95]
	s_setprio 0
	v_cvt_pk_bf16_f32 v52, v72, v73
	v_mov_b32_e32 v54, v73
	v_mov_b32_e32 v55, v74
	v_mov_b32_e32 v73, v75
	v_pk_add_f32 v[54:55], v[54:55], v[72:73]
	v_cvt_pk_bf16_f32 v53, v74, v75
	v_add_f32_e32 v54, v54, v55
	v_add_f32_e32 v58, v54, v56
	s_setprio 1
	s_waitcnt lgkmcnt(0)
	v_mfma_f32_32x32x16_bf16 v[32:47], v[120:123], v[124:127], v[32:47]
	s_setprio 0
	v_cvt_pk_bf16_f32 v54, v76, v77
	v_mov_b32_e32 v56, v77
	v_mov_b32_e32 v57, v78
	v_mov_b32_e32 v77, v79
	v_pk_add_f32 v[56:57], v[56:57], v[76:77]
	v_cvt_pk_bf16_f32 v55, v78, v79
	v_add_f32_e32 v56, v56, v57
	v_add_f32_e32 v104, v56, v58
	v_lshlrev_b32_e32 v56, 8, v193
	v_or3_b32 v105, v56, v200, v199
	ds_read_b64_tr_b16 v[56:57], v105 offset:16384
	ds_read_b64_tr_b16 v[58:59], v105 offset:16896
	ds_read_b64_tr_b16 v[60:61], v105 offset:17408
	ds_read_b64_tr_b16 v[62:63], v105 offset:17920
	ds_read_b64_tr_b16 v[64:65], v105 offset:20480
	ds_read_b64_tr_b16 v[66:67], v105 offset:20992
	ds_read_b64_tr_b16 v[68:69], v105 offset:21504
	ds_read_b64_tr_b16 v[70:71], v105 offset:22016
	s_setprio 1
	s_waitcnt lgkmcnt(6)
	v_mfma_f32_32x32x16_bf16 v[16:31], v[56:59], v[100:103], v[16:31]
	s_setprio 0
	v_exp_f32_e32 v80, v80
	v_exp_f32_e32 v81, v81
	v_exp_f32_e32 v82, v82
	v_exp_f32_e32 v83, v83
	s_setprio 1
	s_waitcnt lgkmcnt(2)
	v_mfma_f32_32x32x16_bf16 v[0:15], v[64:67], v[100:103], v[0:15]
	s_setprio 0
	v_exp_f32_e32 v84, v84
	v_exp_f32_e32 v85, v85
	v_exp_f32_e32 v86, v86
	v_exp_f32_e32 v87, v87
	ds_read_b64_tr_b16 v[56:57], v105 offset:18432
	ds_read_b64_tr_b16 v[58:59], v105 offset:18944
	ds_read_b64_tr_b16 v[64:65], v105 offset:19456
	ds_read_b64_tr_b16 v[66:67], v105 offset:19968
	ds_read_b64_tr_b16 v[72:73], v105 offset:22528
	ds_read_b64_tr_b16 v[74:75], v105 offset:23040
	ds_read_b64_tr_b16 v[76:77], v105 offset:23552
	ds_read_b64_tr_b16 v[78:79], v105 offset:24064
	s_setprio 1
	v_mfma_f32_32x32x16_bf16 v[16:31], v[60:63], v[108:111], v[16:31]
	s_setprio 0
	v_exp_f32_e32 v88, v88
	v_exp_f32_e32 v89, v89
	v_exp_f32_e32 v90, v90
	v_exp_f32_e32 v91, v91
	s_setprio 1
	s_waitcnt lgkmcnt(8)
	v_mfma_f32_32x32x16_bf16 v[0:15], v[68:71], v[108:111], v[0:15]
	s_setprio 0
	v_exp_f32_e32 v92, v92
	v_exp_f32_e32 v93, v93
	v_exp_f32_e32 v94, v94
	v_exp_f32_e32 v95, v95
	s_setprio 1
	s_waitcnt lgkmcnt(6)
	v_mfma_f32_32x32x16_bf16 v[16:31], v[56:59], v[48:51], v[16:31]
	s_setprio 0
	v_exp_f32_e32 v32, v32
	v_exp_f32_e32 v33, v33
	v_exp_f32_e32 v34, v34
	v_exp_f32_e32 v35, v35
	s_setprio 1
	s_waitcnt lgkmcnt(2)
	v_mfma_f32_32x32x16_bf16 v[0:15], v[72:75], v[48:51], v[0:15]
	s_setprio 0
	v_exp_f32_e32 v36, v36
	v_exp_f32_e32 v37, v37
	v_exp_f32_e32 v38, v38
	v_exp_f32_e32 v39, v39
	s_setprio 1
	v_mfma_f32_32x32x16_bf16 v[16:31], v[64:67], v[52:55], v[16:31]
	s_setprio 0
	v_exp_f32_e32 v40, v40
	v_exp_f32_e32 v41, v41
	v_exp_f32_e32 v42, v42
	v_exp_f32_e32 v43, v43
	s_setprio 1
	s_waitcnt lgkmcnt(0)
	v_mfma_f32_32x32x16_bf16 v[0:15], v[76:79], v[52:55], v[0:15]
	s_setprio 0
	v_exp_f32_e32 v44, v44
	v_exp_f32_e32 v45, v45
	v_exp_f32_e32 v46, v46
	v_exp_f32_e32 v47, v47
	s_waitcnt vmcnt(0)
	ds_write_b128 v196, v[96:99] offset:24576
	s_waitcnt lgkmcnt(0)
	s_barrier
	v_add_f32_e32 v50, v80, v81
	v_add_f32_e32 v51, v82, v83
	v_add_f32_e32 v50, v50, v51
	v_cvt_pk_bf16_f32 v48, v80, v81
	v_cvt_pk_bf16_f32 v49, v82, v83
	v_add_f32_e32 v52, 0, v50
	v_add_f32_e32 v53, v84, v85
	v_add_f32_e32 v54, v86, v87
	v_add_f32_e32 v53, v53, v54
	v_cvt_pk_bf16_f32 v50, v84, v85
	v_cvt_pk_bf16_f32 v51, v86, v87
	v_add_f32_e32 v54, v53, v52
	v_add_f32_e32 v55, v88, v89
	v_add_f32_e32 v56, v90, v91
	v_add_f32_e32 v55, v55, v56
	v_cvt_pk_bf16_f32 v52, v88, v89
	v_cvt_pk_bf16_f32 v53, v90, v91
	v_add_f32_e32 v56, v55, v54
	v_add_f32_e32 v57, v92, v93
	v_add_f32_e32 v58, v94, v95
	v_add_f32_e32 v57, v57, v58
	v_cvt_pk_bf16_f32 v54, v92, v93
	v_cvt_pk_bf16_f32 v55, v94, v95
	v_add_f32_e32 v58, v57, v56
	v_cvt_pk_bf16_f32 v56, v32, v33
	v_add_f32_e32 v32, v32, v33
	v_add_f32_e32 v33, v34, v35
	v_add_f32_e32 v32, v32, v33
	v_cvt_pk_bf16_f32 v57, v34, v35
	v_add_f32_e32 v34, v32, v58
	s_nop 0
	v_cvt_pk_bf16_f32 v58, v36, v37
	v_mov_b32_e32 v32, v37
	v_mov_b32_e32 v33, v38
	v_mov_b32_e32 v37, v39
	v_pk_add_f32 v[32:33], v[32:33], v[36:37]
	v_cvt_pk_bf16_f32 v59, v38, v39
	v_add_f32_e32 v32, v32, v33
	v_add_f32_e32 v36, v32, v34
	v_cvt_pk_bf16_f32 v32, v40, v41
	v_mov_b32_e32 v34, v41
	v_mov_b32_e32 v35, v42
	v_mov_b32_e32 v41, v43
	v_pk_add_f32 v[34:35], v[34:35], v[40:41]
	v_cvt_pk_bf16_f32 v33, v42, v43
	v_add_f32_e32 v34, v34, v35
	v_add_f32_e32 v38, v34, v36
	s_nop 0
	v_cvt_pk_bf16_f32 v34, v44, v45
	v_mov_b32_e32 v36, v45
	v_mov_b32_e32 v37, v46
	v_mov_b32_e32 v45, v47
	v_pk_add_f32 v[36:37], v[36:37], v[44:45]
	v_cvt_pk_bf16_f32 v35, v46, v47
	v_add_f32_e32 v36, v36, v37
	v_add_f32_e32 v68, v36, v38
	ds_read_b64_tr_b16 v[36:37], v105 offset:24576
	ds_read_b64_tr_b16 v[38:39], v105 offset:25088
	ds_read_b64_tr_b16 v[40:41], v105 offset:25600
	ds_read_b64_tr_b16 v[42:43], v105 offset:26112
	ds_read_b64_tr_b16 v[44:45], v105 offset:28672
	ds_read_b64_tr_b16 v[46:47], v105 offset:29184
	ds_read_b64_tr_b16 v[60:61], v105 offset:29696
	ds_read_b64_tr_b16 v[62:63], v105 offset:30208
	s_setprio 1
	s_waitcnt lgkmcnt(6)
	v_mfma_f32_32x32x16_bf16 v[16:31], v[36:39], v[48:51], v[16:31]
	s_setprio 0
	s_setprio 1
	s_waitcnt lgkmcnt(2)
	v_mfma_f32_32x32x16_bf16 v[0:15], v[44:47], v[48:51], v[0:15]
	s_setprio 0
	ds_read_b64_tr_b16 v[36:37], v105 offset:26624
	ds_read_b64_tr_b16 v[38:39], v105 offset:27136
	ds_read_b64_tr_b16 v[44:45], v105 offset:27648
	ds_read_b64_tr_b16 v[46:47], v105 offset:28160
	ds_read_b64_tr_b16 v[48:49], v105 offset:30720
	ds_read_b64_tr_b16 v[50:51], v105 offset:31232
	ds_read_b64_tr_b16 v[64:65], v105 offset:31744
	ds_read_b64_tr_b16 v[66:67], v105 offset:32256
	s_setprio 1
	v_mfma_f32_32x32x16_bf16 v[16:31], v[40:43], v[52:55], v[16:31]
	s_setprio 0
	s_setprio 1
	s_waitcnt lgkmcnt(8)
	v_mfma_f32_32x32x16_bf16 v[0:15], v[60:63], v[52:55], v[0:15]
	s_setprio 0
	s_setprio 1
	s_waitcnt lgkmcnt(6)
	v_mfma_f32_32x32x16_bf16 v[16:31], v[36:39], v[56:59], v[16:31]
	s_setprio 0
	s_setprio 1
	s_waitcnt lgkmcnt(2)
	v_mfma_f32_32x32x16_bf16 v[0:15], v[48:51], v[56:59], v[0:15]
	s_setprio 0
	s_setprio 1
	v_mfma_f32_32x32x16_bf16 v[16:31], v[44:47], v[32:35], v[16:31]
	s_setprio 0
	s_setprio 1
	s_waitcnt lgkmcnt(0)
	v_mfma_f32_32x32x16_bf16 v[0:15], v[64:67], v[32:35], v[0:15]
	s_setprio 0
	v_add_f32_e32 v32, v197, v104
	v_add_f32_e32 v32, v32, v68
	ds_bpermute_b32 v33, v168, v32
	s_lshl_b32 s30, s5, 1
	s_waitcnt lgkmcnt(0)
	s_barrier
	v_add_f32_e32 v32, v32, v33
	v_div_scale_f32 v33, s[16:17], v32, v32, 1.0
	v_rcp_f32_e32 v34, v33
	v_div_scale_f32 v35, vcc, 1.0, v32, 1.0
	s_mov_b32 s76, 0
	v_fma_f32 v36, -v33, v34, 1.0
	v_fmac_f32_e32 v34, v36, v34
	v_mul_f32_e32 v36, v35, v34
	v_fma_f32 v37, -v33, v36, v35
	v_fmac_f32_e32 v36, v37, v34
	v_fma_f32 v33, -v33, v36, v35
	v_div_fmas_f32 v33, v33, v34, v36
	v_div_fixup_f32 v32, v33, v32, 1.0
	v_pk_mul_f32 v[26:27], v[32:33], v[26:27] op_sel_hi:[0,1]
	v_pk_mul_f32 v[10:11], v[32:33], v[10:11] op_sel_hi:[0,1]
	v_pk_mul_f32 v[28:29], v[32:33], v[28:29] op_sel_hi:[0,1]
	v_pk_mul_f32 v[12:13], v[32:33], v[12:13] op_sel_hi:[0,1]
	v_pk_mul_f32 v[30:31], v[32:33], v[30:31] op_sel_hi:[0,1]
	v_pk_mul_f32 v[14:15], v[32:33], v[14:15] op_sel_hi:[0,1]
	v_lshl_or_b32 v33, v194, 5, v195
	v_pk_mul_f32 v[0:1], v[32:33], v[0:1] op_sel_hi:[0,1]
	v_pk_mul_f32 v[16:17], v[32:33], v[16:17] op_sel_hi:[0,1]
	v_pk_mul_f32 v[2:3], v[32:33], v[2:3] op_sel_hi:[0,1]
	v_pk_mul_f32 v[44:45], v[0:1], v[0:1]
	v_pk_mul_f32 v[18:19], v[32:33], v[18:19] op_sel_hi:[0,1]
	v_pk_mul_f32 v[42:43], v[2:3], v[2:3]
	v_pk_fma_f32 v[44:45], v[16:17], v[16:17], v[44:45]
	v_pk_fma_f32 v[42:43], v[18:19], v[18:19], v[42:43]
	v_pk_mul_f32 v[4:5], v[32:33], v[4:5] op_sel_hi:[0,1]
	v_add_f32_e32 v41, v44, v45
	v_pk_mul_f32 v[20:21], v[32:33], v[20:21] op_sel_hi:[0,1]
	v_pk_mul_f32 v[48:49], v[4:5], v[4:5]
	v_add_f32_e32 v41, v41, v42
	v_pk_mul_f32 v[6:7], v[32:33], v[6:7] op_sel_hi:[0,1]
	v_pk_fma_f32 v[48:49], v[20:21], v[20:21], v[48:49]
	v_add_f32_e32 v41, v41, v43
	v_pk_mul_f32 v[22:23], v[32:33], v[22:23] op_sel_hi:[0,1]
	v_pk_mul_f32 v[46:47], v[6:7], v[6:7]
	v_add_f32_e32 v41, v41, v48
	v_pk_fma_f32 v[46:47], v[22:23], v[22:23], v[46:47]
	v_pk_mul_f32 v[8:9], v[32:33], v[8:9] op_sel_hi:[0,1]
	v_add_f32_e32 v41, v41, v49
	v_add_u32_e32 v40, s14, v33
	v_pk_mul_f32 v[24:25], v[32:33], v[24:25] op_sel_hi:[0,1]
	v_pk_mul_f32 v[32:33], v[8:9], v[8:9]
	v_add_f32_e32 v41, v41, v46
	v_pk_fma_f32 v[32:33], v[24:25], v[24:25], v[32:33]
	v_add_f32_e32 v41, v41, v47
	v_pk_mul_f32 v[34:35], v[10:11], v[10:11]
	v_add_f32_e32 v32, v41, v32
	v_pk_fma_f32 v[34:35], v[26:27], v[26:27], v[34:35]
	v_add_f32_e32 v32, v32, v33
	v_pk_mul_f32 v[36:37], v[12:13], v[12:13]
	v_add_f32_e32 v32, v32, v34
	v_pk_fma_f32 v[36:37], v[28:29], v[28:29], v[36:37]
	v_add_f32_e32 v32, v32, v35
	v_pk_mul_f32 v[38:39], v[14:15], v[14:15]
	v_add_f32_e32 v32, v32, v36
	v_pk_fma_f32 v[38:39], v[30:31], v[30:31], v[38:39]
	v_add_f32_e32 v32, v32, v37
	v_add_f32_e32 v32, v32, v38
	v_add_f32_e32 v34, v32, v39
	ds_bpermute_b32 v35, v168, v34
	v_ashrrev_i32_e32 v41, 31, v40
	v_lshlrev_b64 v[32:33], 11, v[40:41]
	v_lshl_add_u64 v[32:33], s[46:47], 0, v[32:33]
	v_lshl_add_u64 v[32:33], v[32:33], 0, s[30:31]
	s_waitcnt lgkmcnt(0)
	v_add_f32_e32 v34, v34, v35
	v_fmamk_f32 v34, v34, 0x3c800000, v172
	v_mul_f32_e32 v35, 0x4b800000, v34
	v_cmp_gt_f32_e32 vcc, s4, v34
	v_lshlrev_b32_e32 v168, 3, v193
	v_lshl_add_u64 v[32:33], v[32:33], 0, v[168:169]
	v_cndmask_b32_e32 v34, v34, v35, vcc
	v_rsq_f32_e32 v34, v34
	s_mov_b32 s78, 0
	s_mov_b32 s80, 0
	s_mov_b32 s82, 0
	v_mul_f32_e32 v35, 0x45800000, v34
	v_cndmask_b32_e32 v34, v34, v35, vcc
	v_pk_mul_f32 v[16:17], v[34:35], v[16:17] op_sel_hi:[0,1]
	v_pk_mul_f32 v[18:19], v[34:35], v[18:19] op_sel_hi:[0,1]
	v_pk_mul_f32 v[0:1], v[34:35], v[0:1] op_sel_hi:[0,1]
	v_pk_mul_f32 v[2:3], v[34:35], v[2:3] op_sel_hi:[0,1]
	v_cvt_pk_bf16_f32 v16, v16, v17
	v_cvt_pk_bf16_f32 v17, v18, v19
	v_cvt_pk_bf16_f32 v0, v0, v1
	v_cvt_pk_bf16_f32 v1, v2, v3
	global_store_dwordx2 v[32:33], v[16:17], off offset:512
	v_pk_mul_f32 v[16:17], v[34:35], v[20:21] op_sel_hi:[0,1]
	v_pk_mul_f32 v[18:19], v[34:35], v[22:23] op_sel_hi:[0,1]
	global_store_dwordx2 v[32:33], v[0:1], off offset:576
	v_pk_mul_f32 v[0:1], v[34:35], v[4:5] op_sel_hi:[0,1]
	v_pk_mul_f32 v[2:3], v[34:35], v[6:7] op_sel_hi:[0,1]
	v_cvt_pk_bf16_f32 v16, v16, v17
	v_cvt_pk_bf16_f32 v17, v18, v19
	v_cvt_pk_bf16_f32 v0, v0, v1
	v_cvt_pk_bf16_f32 v1, v2, v3
	global_store_dwordx2 v[32:33], v[16:17], off offset:528
	v_pk_mul_f32 v[16:17], v[34:35], v[24:25] op_sel_hi:[0,1]
	v_pk_mul_f32 v[18:19], v[34:35], v[26:27] op_sel_hi:[0,1]
	global_store_dwordx2 v[32:33], v[0:1], off offset:592
	v_pk_mul_f32 v[0:1], v[34:35], v[8:9] op_sel_hi:[0,1]
	v_pk_mul_f32 v[2:3], v[34:35], v[10:11] op_sel_hi:[0,1]
	v_cvt_pk_bf16_f32 v16, v16, v17
	v_cvt_pk_bf16_f32 v17, v18, v19
	v_cvt_pk_bf16_f32 v0, v0, v1
	v_cvt_pk_bf16_f32 v1, v2, v3
	global_store_dwordx2 v[32:33], v[16:17], off offset:544
	v_pk_mul_f32 v[16:17], v[34:35], v[28:29] op_sel_hi:[0,1]
	v_pk_mul_f32 v[18:19], v[34:35], v[30:31] op_sel_hi:[0,1]
	global_store_dwordx2 v[32:33], v[0:1], off offset:608
	v_pk_mul_f32 v[0:1], v[34:35], v[12:13] op_sel_hi:[0,1]
	v_pk_mul_f32 v[2:3], v[34:35], v[14:15] op_sel_hi:[0,1]
	s_mov_b32 s68, 0
	s_mov_b32 s70, 0
	s_mov_b32 s72, 0
	v_readlane_b32 s74, v254, 52
	v_cvt_pk_bf16_f32 v16, v16, v17
	v_cvt_pk_bf16_f32 v17, v18, v19
	v_cvt_pk_bf16_f32 v0, v0, v1
	v_cvt_pk_bf16_f32 v1, v2, v3
	s_mov_b32 s77, 0x40732000
	s_mov_b32 s79, 0x40756000
	s_mov_b32 s81, 0x4077c000
	s_mov_b32 s83, 0x407a4000
	s_mov_b32 s69, 0x407ce000
	s_mov_b32 s71, 0x407fa000
	s_mov_b32 s73, 0x40814000
	v_readlane_b32 s75, v254, 53
	global_store_dwordx2 v[32:33], v[16:17], off offset:560
	global_store_dwordx2 v[32:33], v[0:1], off offset:624
	s_branch .LBB0_106
